# attention steady-state loop hand-rescheduled: K/V fragment prefetch, permlane32_swap row-max, in-place P, MFMA-VALU interleave
# speedup vs baseline: 1.0038x; 1.0038x over previous
; __device__ void attn_phase(const Params& p, bool last, char* shm, int w0) {
;     ...
;         const bf16_t* Kb = Ks + buf * 64 * KSTR; const bf16_t* Vb = Vs + buf * 64 * VSTR;
; #pragma unroll
;         for (int k2 = 0; k2 < 2; ++k2) {
;           f32x16 st[2];
; #pragma unroll
;           for (int j = 0; j < 2; ++j)
; #pragma unroll
;             for (int e = 0; e < 16; ++e) st[j][e] = -mrun[j];
; #pragma unroll
;           for (int ks = 0; ks < 6; ++ks) {
;             const bf16x8 kf = *(const bf16x8*)(Kb + (k2 * 32 + lq) * KSTR + ks * 16 + hb * 8);
;             st[0] = __builtin_amdgcn_mfma_f32_32x32x16_bf16(kf, qf[0][ks], st[0], 0, 0, 0);
;             st[1] = __builtin_amdgcn_mfma_f32_32x32x16_bf16(kf, qf[1][ks], st[1], 0, 0, 0);
;           }
;           bf16x8 pf[2][2];
; #pragma unroll
;           for (int qt = 0; qt < 2; ++qt) {
;             float mx = st[qt][0];
; #pragma unroll
;             for (int e = 1; e < 16; ++e) mx = fmaxf(mx, st[qt][e]);
;             mx = fmaxf(mx, __shfl_xor(mx, 32));
;             const bool first = (kt == 0 && k2 == 0);
;             if (first || __builtin_amdgcn_ballot_w64(mx > 6.f) != 0ull) {
;               const float delta = first ? mx : fmaxf(mx, 0.f);
;               const float alpha = first ? 1.f : __builtin_amdgcn_exp2f(-delta);
;               mrun[qt] += delta;
; #pragma unroll
;               for (int e = 0; e < 16; ++e) st[qt][e] -= delta;
;               lrun[qt] *= alpha;
; #pragma unroll
;               for (int dt = 0; dt < 2; ++dt)
; #pragma unroll
;                 for (int e = 0; e < 16; ++e) ot[dt][qt][e] *= alpha;
;             }
;             float ls = 0.f;
; #pragma unroll
;             for (int s2 = 0; s2 < 2; ++s2) {
;               const int g0 = s2 * 2; bf16x8 f;
; #pragma unroll
;               for (int j = 0; j < 4; j += 2) {
;                 const float p0 = __builtin_amdgcn_exp2f(st[qt][g0 * 4 + j]), p1 = __builtin_amdgcn_exp2f(st[qt][g0 * 4 + j + 1]);
;                 const float p2 = __builtin_amdgcn_exp2f(st[qt][(g0 + 1) * 4 + j]), p3 = __builtin_amdgcn_exp2f(st[qt][(g0 + 1) * 4 + j + 1]);
;                 ls += (p0 + p1) + (p2 + p3);
;                 const unsigned ww0 = pk2(p0, p1), ww1 = pk2(p2, p3);
;                 f[j] = (short)(ww0 & 0xffffu); f[j + 1] = (short)(ww0 >> 16); f[4 + j] = (short)(ww1 & 0xffffu); f[4 + j + 1] = (short)(ww1 >> 16);
;               }
.LBB0_651:
	s_or_b64 exec, exec, s[0:1]
	global_load_dwordx4 v[6:9], v[220:221], off
	s_add_i32 s10, s10, 1
	s_and_b32 s11, s10, 1
	s_and_saveexec_b64 s[0:1], s[8:9]
	s_cbranch_execz .LBB0_661
	s_mul_i32 s12, s11, 0x3400
	v_add_u32_e32 v0, s12, v237
	v_add_u32_e32 v215, v0, v240
	s_mul_i32 s12, s11, 0x2400
	ds_read_b128 v[180:183], v215 offset:0
	ds_read_b128 v[184:187], v215 offset:32
	ds_read_b128 v[188:191], v215 offset:64
	ds_read_b128 v[228:231], v215 offset:96
	ds_read_b128 v[80:83], v215 offset:128
	ds_read_b128 v[84:87], v215 offset:160
	v_add_u32_e32 v0, s12, v238
	v_add_u32_e32 v218, v0, v241
	v_add_u32_e32 v233, v0, v239
	v_add_u32_e32 v218, 0x6800, v218
	v_add_u32_e32 v233, 0x6800, v233
	ds_read2_b64 v[88:91], v218 offset1:2
	ds_read2_b64 v[242:245], v233 offset1:2
	ds_read2_b64 v[92:95], v218 offset0:4 offset1:6
	ds_read2_b64 v[246:249], v233 offset0:4 offset1:6
	v_xor_b32_e32 v224, 0x80000000, v217
	v_xor_b32_e32 v225, 0x80000000, v219
	v_mov_b32_e32 v96, v224
	v_mov_b32_e32 v97, v224
	v_mov_b32_e32 v98, v224
	v_mov_b32_e32 v99, v224
	v_mov_b32_e32 v100, v224
	v_mov_b32_e32 v101, v224
	v_mov_b32_e32 v102, v224
	v_mov_b32_e32 v103, v224
	v_mov_b32_e32 v104, v224
	v_mov_b32_e32 v105, v224
	v_mov_b32_e32 v106, v224
	v_mov_b32_e32 v107, v224
	v_mov_b32_e32 v108, v224
	v_mov_b32_e32 v109, v224
	v_mov_b32_e32 v110, v224
	v_mov_b32_e32 v111, v224
	v_mov_b32_e32 v112, v225
	v_mov_b32_e32 v113, v225
	v_mov_b32_e32 v114, v225
	v_mov_b32_e32 v115, v225
	v_mov_b32_e32 v116, v225
	v_mov_b32_e32 v117, v225
	v_mov_b32_e32 v118, v225
	v_mov_b32_e32 v119, v225
	v_mov_b32_e32 v120, v225
	v_mov_b32_e32 v121, v225
	v_mov_b32_e32 v122, v225
	v_mov_b32_e32 v123, v225
	v_mov_b32_e32 v124, v225
	v_mov_b32_e32 v125, v225
	v_mov_b32_e32 v126, v225
	v_mov_b32_e32 v127, v225
	s_waitcnt lgkmcnt(9)
	v_mfma_f32_32x32x16_bf16 v[96:111], v[180:183], v[128:131], v[96:111]
	s_waitcnt lgkmcnt(8)
	v_mfma_f32_32x32x16_bf16 v[96:111], v[184:187], v[132:135], v[96:111]
	s_waitcnt lgkmcnt(7)
	v_mfma_f32_32x32x16_bf16 v[96:111], v[188:191], v[136:139], v[96:111]
	s_waitcnt lgkmcnt(6)
	v_mfma_f32_32x32x16_bf16 v[96:111], v[228:231], v[140:143], v[96:111]
	s_waitcnt lgkmcnt(5)
	v_mfma_f32_32x32x16_bf16 v[96:111], v[80:83], v[144:147], v[96:111]
	s_waitcnt lgkmcnt(4)
	v_mfma_f32_32x32x16_bf16 v[96:111], v[84:87], v[148:151], v[96:111]
	v_mfma_f32_32x32x16_bf16 v[112:127], v[180:183], v[152:155], v[112:127]
	ds_read_b128 v[180:183], v215 offset:6656
	v_mfma_f32_32x32x16_bf16 v[112:127], v[184:187], v[156:159], v[112:127]
	ds_read_b128 v[184:187], v215 offset:6688
	v_mfma_f32_32x32x16_bf16 v[112:127], v[188:191], v[160:163], v[112:127]
	ds_read_b128 v[188:191], v215 offset:6720
	v_mfma_f32_32x32x16_bf16 v[112:127], v[228:231], v[164:167], v[112:127]
	ds_read_b128 v[228:231], v215 offset:6752
	v_mfma_f32_32x32x16_bf16 v[112:127], v[80:83], v[168:171], v[112:127]
	ds_read_b128 v[80:83], v215 offset:6784
	v_mfma_f32_32x32x16_bf16 v[112:127], v[84:87], v[172:175], v[112:127]
	ds_read_b128 v[84:87], v215 offset:6816
	v_max3_f32 v10, v96, v97, v98
	v_max3_f32 v10, v10, v99, v100
	v_max3_f32 v10, v10, v101, v102
	v_max3_f32 v10, v10, v103, v104
	v_max3_f32 v10, v10, v105, v106
	v_max3_f32 v10, v10, v107, v108
	v_max3_f32 v10, v10, v109, v110
	v_max_f32_e32 v10, v10, v111
	s_nop 2
	v_max3_f32 v11, v112, v113, v114
	v_max3_f32 v11, v11, v115, v116
	v_max3_f32 v11, v11, v117, v118
	v_max3_f32 v11, v11, v119, v120
	v_max3_f32 v11, v11, v121, v122
	v_max3_f32 v11, v11, v123, v124
	v_max3_f32 v11, v11, v125, v126
	v_max_f32_e32 v11, v11, v127
	v_mov_b32_e32 v12, v10
	v_mov_b32_e32 v13, v11
	s_nop 1
	v_permlane32_swap_b32_e32 v12, v10
	v_permlane32_swap_b32_e32 v13, v11
	v_max_f32_e32 v10, v10, v12
	v_max_f32_e32 v11, v11, v13
	v_max_f32_e32 v0, v10, v11
	v_cmp_lt_f32_e32 vcc, s97, v0
	s_cbranch_vccnz .Lattn_rare_a
.Lattn_back_a:
	v_xor_b32_e32 v224, 0x80000000, v217
	v_xor_b32_e32 v225, 0x80000000, v219
	v_exp_f32_e32 v96, v96
	v_exp_f32_e32 v97, v97
	v_exp_f32_e32 v100, v100
	v_exp_f32_e32 v101, v101
	v_exp_f32_e32 v98, v98
	v_exp_f32_e32 v99, v99
	v_exp_f32_e32 v102, v102
	v_exp_f32_e32 v103, v103
	v_add_f32_e32 v0, v97, v96
	v_add_f32_e32 v227, v101, v100
	v_add_f32_e32 v0, v227, v0
	v_add_f32_e32 v227, v99, v98
	v_add_f32_e32 v232, v103, v102
	v_add_f32_e32 v227, v232, v227
	v_add_f32_e32 v192, v227, v0
	v_cvt_pk_bf16_f32 v96, v96, v97
	v_cvt_pk_bf16_f32 v97, v98, v99
	v_cvt_pk_bf16_f32 v98, v100, v101
	v_cvt_pk_bf16_f32 v99, v102, v103
	v_exp_f32_e32 v104, v104
	v_exp_f32_e32 v105, v105
	s_waitcnt lgkmcnt(8)
	v_mfma_f32_32x32x16_bf16 v[48:63], v[88:91], v[96:99], v[48:63]
	v_mfma_f32_32x32x16_bf16 v[64:79], v[242:245], v[96:99], v[64:79]
	v_exp_f32_e32 v108, v108
	v_exp_f32_e32 v109, v109
	v_exp_f32_e32 v106, v106
	v_exp_f32_e32 v107, v107
	v_exp_f32_e32 v110, v110
	v_exp_f32_e32 v111, v111
	v_add_f32_e32 v0, v105, v104
	v_add_f32_e32 v227, v109, v108
	v_add_f32_e32 v0, v227, v0
	v_add_f32_e32 v227, v107, v106
	v_add_f32_e32 v232, v111, v110
	v_add_f32_e32 v227, v232, v227
	v_add_f32_e32 v192, v0, v192
	v_add_f32_e32 v192, v227, v192
	v_cvt_pk_bf16_f32 v104, v104, v105
	v_cvt_pk_bf16_f32 v105, v106, v107
	v_cvt_pk_bf16_f32 v106, v108, v109
	v_cvt_pk_bf16_f32 v107, v110, v111
	v_add_f32_e32 v213, v213, v192
	v_exp_f32_e32 v112, v112
	v_exp_f32_e32 v113, v113
	s_waitcnt lgkmcnt(6)
; __device__ void attn_phase(const Params& p, bool last, char* shm, int w0) {
;     ...
;             for (int e = 0; e < 16; ++e) st[j][e] = -mrun[j];
; #pragma unroll
;           for (int ks = 0; ks < 6; ++ks) {
;             const bf16x8 kf = *(const bf16x8*)(Kb + (k2 * 32 + lq) * KSTR + ks * 16 + hb * 8);
;             st[0] = __builtin_amdgcn_mfma_f32_32x32x16_bf16(kf, qf[0][ks], st[0], 0, 0, 0);
;             st[1] = __builtin_amdgcn_mfma_f32_32x32x16_bf16(kf, qf[1][ks], st[1], 0, 0, 0);
;           }
;           bf16x8 pf[2][2];
; #pragma unroll
;           for (int qt = 0; qt < 2; ++qt) {
;             float mx = st[qt][0];
; #pragma unroll
;             for (int e = 1; e < 16; ++e) mx = fmaxf(mx, st[qt][e]);
;             mx = fmaxf(mx, __shfl_xor(mx, 32));
;             const bool first = (kt == 0 && k2 == 0);
;             if (first || __builtin_amdgcn_ballot_w64(mx > 6.f) != 0ull) {
;               const float delta = first ? mx : fmaxf(mx, 0.f);
;               const float alpha = first ? 1.f : __builtin_amdgcn_exp2f(-delta);
;               mrun[qt] += delta;
; #pragma unroll
;               for (int e = 0; e < 16; ++e) st[qt][e] -= delta;
;               lrun[qt] *= alpha;
; #pragma unroll
;               for (int dt = 0; dt < 2; ++dt)
; #pragma unroll
;                 for (int e = 0; e < 16; ++e) ot[dt][qt][e] *= alpha;
;             }
;             float ls = 0.f;
; #pragma unroll
;             for (int s2 = 0; s2 < 2; ++s2) {
;               const int g0 = s2 * 2; bf16x8 f;
; #pragma unroll
;               for (int j = 0; j < 4; j += 2) {
;                 const float p0 = __builtin_amdgcn_exp2f(st[qt][g0 * 4 + j]), p1 = __builtin_amdgcn_exp2f(st[qt][g0 * 4 + j + 1]);
;                 const float p2 = __builtin_amdgcn_exp2f(st[qt][(g0 + 1) * 4 + j]), p3 = __builtin_amdgcn_exp2f(st[qt][(g0 + 1) * 4 + j + 1]);
;                 ls += (p0 + p1) + (p2 + p3);
;                 const unsigned ww0 = pk2(p0, p1), ww1 = pk2(p2, p3);
;                 f[j] = (short)(ww0 & 0xffffu); f[j + 1] = (short)(ww0 >> 16); f[4 + j] = (short)(ww1 & 0xffffu); f[4 + j + 1] = (short)(ww1 >> 16);
;               }
;               pf[qt][s2] = f;
;             }
;             lrun[qt] += ls;
;           }
; #pragma unroll
;           for (int dt = 0; dt < 2; ++dt)
; #pragma unroll
;             for (int s2 = 0; s2 < 2; ++s2) {
	v_mfma_f32_32x32x16_bf16 v[48:63], v[92:95], v[104:107], v[48:63]
	v_mfma_f32_32x32x16_bf16 v[64:79], v[246:249], v[104:107], v[64:79]
	v_exp_f32_e32 v116, v116
	v_exp_f32_e32 v117, v117
	v_exp_f32_e32 v114, v114
	v_exp_f32_e32 v115, v115
	v_exp_f32_e32 v118, v118
	v_exp_f32_e32 v119, v119
	v_add_f32_e32 v0, v113, v112
	v_add_f32_e32 v227, v117, v116
	v_add_f32_e32 v0, v227, v0
	v_add_f32_e32 v227, v115, v114
	v_add_f32_e32 v232, v119, v118
	v_add_f32_e32 v227, v232, v227
	v_add_f32_e32 v193, v227, v0
	v_cvt_pk_bf16_f32 v112, v112, v113
	v_cvt_pk_bf16_f32 v113, v114, v115
	v_cvt_pk_bf16_f32 v114, v116, v117
	v_cvt_pk_bf16_f32 v115, v118, v119
	v_mov_b32_e32 v100, v224
	v_mov_b32_e32 v101, v224
	v_mov_b32_e32 v102, v224
	v_mov_b32_e32 v103, v224
	v_mov_b32_e32 v108, v224
	v_mov_b32_e32 v109, v224
	v_mov_b32_e32 v110, v224
	v_mov_b32_e32 v111, v224
	v_exp_f32_e32 v120, v120
	v_exp_f32_e32 v121, v121
	v_mfma_f32_32x32x16_bf16 v[16:31], v[88:91], v[112:115], v[16:31]
	v_mfma_f32_32x32x16_bf16 v[32:47], v[242:245], v[112:115], v[32:47]
	v_exp_f32_e32 v124, v124
	v_exp_f32_e32 v125, v125
	v_exp_f32_e32 v122, v122
	v_exp_f32_e32 v123, v123
	v_exp_f32_e32 v126, v126
	v_exp_f32_e32 v127, v127
	v_add_f32_e32 v0, v121, v120
	v_add_f32_e32 v227, v125, v124
	v_add_f32_e32 v0, v227, v0
	v_add_f32_e32 v227, v123, v122
	v_add_f32_e32 v232, v127, v126
	v_add_f32_e32 v227, v232, v227
	v_add_f32_e32 v193, v0, v193
	v_add_f32_e32 v193, v227, v193
	v_cvt_pk_bf16_f32 v120, v120, v121
	v_cvt_pk_bf16_f32 v121, v122, v123
	v_cvt_pk_bf16_f32 v122, v124, v125
	v_cvt_pk_bf16_f32 v123, v126, v127
	v_add_f32_e32 v216, v216, v193
	v_mov_b32_e32 v96, v224
	v_mov_b32_e32 v97, v224
	v_mov_b32_e32 v98, v224
	v_mov_b32_e32 v99, v224
	v_mov_b32_e32 v104, v224
	v_mov_b32_e32 v105, v224
	v_mov_b32_e32 v106, v224
	v_mov_b32_e32 v107, v224
	v_mfma_f32_32x32x16_bf16 v[16:31], v[92:95], v[120:123], v[16:31]
	v_mfma_f32_32x32x16_bf16 v[32:47], v[246:249], v[120:123], v[32:47]
	ds_read2_b64 v[88:91], v218 offset0:8 offset1:10
	ds_read2_b64 v[242:245], v233 offset0:8 offset1:10
	ds_read2_b64 v[92:95], v218 offset0:12 offset1:14
	ds_read2_b64 v[246:249], v233 offset0:12 offset1:14
	v_mov_b32_e32 v116, v225
	v_mov_b32_e32 v117, v225
	v_mov_b32_e32 v118, v225
	v_mov_b32_e32 v119, v225
	v_mov_b32_e32 v124, v225
	v_mov_b32_e32 v125, v225
	v_mov_b32_e32 v126, v225
	v_mov_b32_e32 v127, v225
	v_mov_b32_e32 v112, v225
	v_mov_b32_e32 v113, v225
	v_mov_b32_e32 v114, v225
	v_mov_b32_e32 v115, v225
	v_mov_b32_e32 v120, v225
	v_mov_b32_e32 v121, v225
	v_mov_b32_e32 v122, v225
	v_mov_b32_e32 v123, v225
	s_waitcnt lgkmcnt(9)
	v_mfma_f32_32x32x16_bf16 v[96:111], v[180:183], v[128:131], v[96:111]
	s_waitcnt lgkmcnt(8)
	v_mfma_f32_32x32x16_bf16 v[96:111], v[184:187], v[132:135], v[96:111]
	s_waitcnt lgkmcnt(7)
	v_mfma_f32_32x32x16_bf16 v[96:111], v[188:191], v[136:139], v[96:111]
	s_waitcnt lgkmcnt(6)
	v_mfma_f32_32x32x16_bf16 v[96:111], v[228:231], v[140:143], v[96:111]
	s_waitcnt lgkmcnt(5)
	v_mfma_f32_32x32x16_bf16 v[96:111], v[80:83], v[144:147], v[96:111]
	s_waitcnt lgkmcnt(4)
	v_mfma_f32_32x32x16_bf16 v[96:111], v[84:87], v[148:151], v[96:111]
	v_mfma_f32_32x32x16_bf16 v[112:127], v[180:183], v[152:155], v[112:127]
	v_mfma_f32_32x32x16_bf16 v[112:127], v[184:187], v[156:159], v[112:127]
	v_mfma_f32_32x32x16_bf16 v[112:127], v[188:191], v[160:163], v[112:127]
	v_mfma_f32_32x32x16_bf16 v[112:127], v[228:231], v[164:167], v[112:127]
	v_mfma_f32_32x32x16_bf16 v[112:127], v[80:83], v[168:171], v[112:127]
	v_mfma_f32_32x32x16_bf16 v[112:127], v[84:87], v[172:175], v[112:127]
	s_nop 5
	v_max3_f32 v10, v96, v97, v98
	v_max3_f32 v10, v10, v99, v100
	v_max3_f32 v10, v10, v101, v102
	v_max3_f32 v10, v10, v103, v104
	v_max3_f32 v10, v10, v105, v106
	v_max3_f32 v10, v10, v107, v108
	v_max3_f32 v10, v10, v109, v110
	v_max_f32_e32 v10, v10, v111
	v_max3_f32 v11, v112, v113, v114
	v_max3_f32 v11, v11, v115, v116
	v_max3_f32 v11, v11, v117, v118
	v_max3_f32 v11, v11, v119, v120
	v_max3_f32 v11, v11, v121, v122
	v_max3_f32 v11, v11, v123, v124
	v_max3_f32 v11, v11, v125, v126
	v_max_f32_e32 v11, v11, v127
	v_mov_b32_e32 v12, v10
	v_mov_b32_e32 v13, v11
	s_nop 1
	v_permlane32_swap_b32_e32 v12, v10
	v_permlane32_swap_b32_e32 v13, v11
	v_max_f32_e32 v10, v10, v12
	v_max_f32_e32 v11, v11, v13
	v_max_f32_e32 v0, v10, v11
	v_cmp_lt_f32_e32 vcc, s97, v0
	s_cbranch_vccnz .Lattn_rare_b
; __device__ __forceinline__ unsigned pk2(float lo, float hi) { const f2_t v = {lo, hi}; return __builtin_bit_cast(unsigned, __builtin_convertvector(v, bf2_t)); }
; __device__ void attn_phase(const Params& p, bool last, char* shm, int w0) {
;     ...
;             if (first || __builtin_amdgcn_ballot_w64(mx > 6.f) != 0ull) {
;               const float delta = first ? mx : fmaxf(mx, 0.f);
;               const float alpha = first ? 1.f : __builtin_amdgcn_exp2f(-delta);
;               mrun[qt] += delta;
; #pragma unroll
;               for (int e = 0; e < 16; ++e) st[qt][e] -= delta;
;               lrun[qt] *= alpha;
; #pragma unroll
;               for (int dt = 0; dt < 2; ++dt)
; #pragma unroll
;                 for (int e = 0; e < 16; ++e) ot[dt][qt][e] *= alpha;
;             }
;             float ls = 0.f;
; #pragma unroll
;             for (int s2 = 0; s2 < 2; ++s2) {
;               const int g0 = s2 * 2; bf16x8 f;
; #pragma unroll
;               for (int j = 0; j < 4; j += 2) {
;                 const float p0 = __builtin_amdgcn_exp2f(st[qt][g0 * 4 + j]), p1 = __builtin_amdgcn_exp2f(st[qt][g0 * 4 + j + 1]);
;                 const float p2 = __builtin_amdgcn_exp2f(st[qt][(g0 + 1) * 4 + j]), p3 = __builtin_amdgcn_exp2f(st[qt][(g0 + 1) * 4 + j + 1]);
;                 ls += (p0 + p1) + (p2 + p3);
;                 const unsigned ww0 = pk2(p0, p1), ww1 = pk2(p2, p3);
;                 f[j] = (short)(ww0 & 0xffffu); f[j + 1] = (short)(ww0 >> 16); f[4 + j] = (short)(ww1 & 0xffffu); f[4 + j + 1] = (short)(ww1 >> 16);
;               }
;               pf[qt][s2] = f;
;             }
;             lrun[qt] += ls;
;           }
; #pragma unroll
;           for (int dt = 0; dt < 2; ++dt)
; #pragma unroll
;             for (int s2 = 0; s2 < 2; ++s2) {
;               const bf16_t* vp = Vb + (dt * 32 + lq) * VSTR + (k2 * 2 + s2) * 16 + hb * 4;
;               const bf16x4 v0 = *(const bf16x4*)vp, v1 = *(const bf16x4*)(vp + 8);
;               bf16x8 vf; vf[0] = v0[0]; vf[1] = v0[1]; vf[2] = v0[2]; vf[3] = v0[3]; vf[4] = v1[0]; vf[5] = v1[1]; vf[6] = v1[2]; vf[7] = v1[3];
;               ot[dt][0] = __builtin_amdgcn_mfma_f32_32x32x16_bf16(vf, pf[0][s2], ot[dt][0], 0, 0, 0);
;               ot[dt][1] = __builtin_amdgcn_mfma_f32_32x32x16_bf16(vf, pf[1][s2], ot[dt][1], 0, 0, 0);
;             }
.Lattn_back_b:
	v_exp_f32_e32 v96, v96
	v_exp_f32_e32 v97, v97
	v_exp_f32_e32 v100, v100
	v_exp_f32_e32 v101, v101
	v_exp_f32_e32 v98, v98
	v_exp_f32_e32 v99, v99
	v_exp_f32_e32 v102, v102
	v_exp_f32_e32 v103, v103
	v_add_f32_e32 v0, v97, v96
	v_add_f32_e32 v227, v101, v100
	v_add_f32_e32 v0, v227, v0
	v_add_f32_e32 v227, v99, v98
	v_add_f32_e32 v232, v103, v102
	v_add_f32_e32 v227, v232, v227
	v_add_f32_e32 v192, v227, v0
	v_cvt_pk_bf16_f32 v96, v96, v97
	v_cvt_pk_bf16_f32 v97, v98, v99
	v_cvt_pk_bf16_f32 v98, v100, v101
	v_cvt_pk_bf16_f32 v99, v102, v103
	v_exp_f32_e32 v104, v104
	v_exp_f32_e32 v105, v105
	s_waitcnt lgkmcnt(2)
	v_mfma_f32_32x32x16_bf16 v[48:63], v[88:91], v[96:99], v[48:63]
	v_mfma_f32_32x32x16_bf16 v[64:79], v[242:245], v[96:99], v[64:79]
	v_exp_f32_e32 v108, v108
	v_exp_f32_e32 v109, v109
	v_exp_f32_e32 v106, v106
	v_exp_f32_e32 v107, v107
	v_exp_f32_e32 v110, v110
	v_exp_f32_e32 v111, v111
	v_add_f32_e32 v0, v105, v104
	v_add_f32_e32 v227, v109, v108
	v_add_f32_e32 v0, v227, v0
	v_add_f32_e32 v227, v107, v106
	v_add_f32_e32 v232, v111, v110
	v_add_f32_e32 v227, v232, v227
	v_add_f32_e32 v192, v0, v192
	v_add_f32_e32 v192, v227, v192
	v_cvt_pk_bf16_f32 v104, v104, v105
	v_cvt_pk_bf16_f32 v105, v106, v107
	v_cvt_pk_bf16_f32 v106, v108, v109
	v_cvt_pk_bf16_f32 v107, v110, v111
	v_add_f32_e32 v213, v213, v192
	v_exp_f32_e32 v112, v112
	v_exp_f32_e32 v113, v113
	s_waitcnt lgkmcnt(0)
	v_mfma_f32_32x32x16_bf16 v[48:63], v[92:95], v[104:107], v[48:63]
	v_mfma_f32_32x32x16_bf16 v[64:79], v[246:249], v[104:107], v[64:79]
	v_exp_f32_e32 v116, v116
	v_exp_f32_e32 v117, v117
	v_exp_f32_e32 v114, v114
	v_exp_f32_e32 v115, v115
	v_exp_f32_e32 v118, v118
	v_exp_f32_e32 v119, v119
	v_add_f32_e32 v0, v113, v112
	v_add_f32_e32 v227, v117, v116
	v_add_f32_e32 v0, v227, v0
	v_add_f32_e32 v227, v115, v114
	v_add_f32_e32 v232, v119, v118
	v_add_f32_e32 v227, v232, v227
	v_add_f32_e32 v193, v227, v0
	v_cvt_pk_bf16_f32 v112, v112, v113
	v_cvt_pk_bf16_f32 v113, v114, v115
	v_cvt_pk_bf16_f32 v114, v116, v117
	v_cvt_pk_bf16_f32 v115, v118, v119
	v_exp_f32_e32 v120, v120
	v_exp_f32_e32 v121, v121
	v_mfma_f32_32x32x16_bf16 v[16:31], v[88:91], v[112:115], v[16:31]
	v_mfma_f32_32x32x16_bf16 v[32:47], v[242:245], v[112:115], v[32:47]
	v_exp_f32_e32 v124, v124
	v_exp_f32_e32 v125, v125
	v_exp_f32_e32 v122, v122
	v_exp_f32_e32 v123, v123
	v_exp_f32_e32 v126, v126
	v_exp_f32_e32 v127, v127
	v_add_f32_e32 v0, v121, v120
	v_add_f32_e32 v227, v125, v124
	v_add_f32_e32 v0, v227, v0
	v_add_f32_e32 v227, v123, v122
	v_add_f32_e32 v232, v127, v126
	v_add_f32_e32 v227, v232, v227
	v_add_f32_e32 v193, v0, v193
	v_add_f32_e32 v193, v227, v193
	v_cvt_pk_bf16_f32 v120, v120, v121
	v_cvt_pk_bf16_f32 v121, v122, v123
	v_cvt_pk_bf16_f32 v122, v124, v125
	v_cvt_pk_bf16_f32 v123, v126, v127
	v_add_f32_e32 v216, v216, v193
	s_nop 0
	v_mfma_f32_32x32x16_bf16 v[16:31], v[92:95], v[120:123], v[16:31]
	v_mfma_f32_32x32x16_bf16 v[32:47], v[246:249], v[120:123], v[32:47]
	s_branch .Lattn_body_end
.Lattn_rare_a:
	v_cmp_lt_f32_e32 vcc, s97, v10
	s_cbranch_vccz .Lattn_rare_a_1
	v_max_f32_e32 v10, 0, v10
	v_exp_f32_e64 v12, -v10
	v_add_f32_e32 v217, v217, v10
	v_pk_add_f32 v[96:97], v[96:97], v[10:11] op_sel_hi:[1,0] neg_lo:[0,1] neg_hi:[0,1]
	v_pk_add_f32 v[98:99], v[98:99], v[10:11] op_sel_hi:[1,0] neg_lo:[0,1] neg_hi:[0,1]
	v_pk_add_f32 v[100:101], v[100:101], v[10:11] op_sel_hi:[1,0] neg_lo:[0,1] neg_hi:[0,1]
	v_pk_add_f32 v[102:103], v[102:103], v[10:11] op_sel_hi:[1,0] neg_lo:[0,1] neg_hi:[0,1]
	v_pk_add_f32 v[104:105], v[104:105], v[10:11] op_sel_hi:[1,0] neg_lo:[0,1] neg_hi:[0,1]
	v_pk_add_f32 v[106:107], v[106:107], v[10:11] op_sel_hi:[1,0] neg_lo:[0,1] neg_hi:[0,1]
	v_pk_add_f32 v[108:109], v[108:109], v[10:11] op_sel_hi:[1,0] neg_lo:[0,1] neg_hi:[0,1]
	v_pk_add_f32 v[110:111], v[110:111], v[10:11] op_sel_hi:[1,0] neg_lo:[0,1] neg_hi:[0,1]
	v_mul_f32_e32 v213, v213, v12
	v_pk_mul_f32 v[62:63], v[62:63], v[12:13] op_sel_hi:[1,0]
	v_pk_mul_f32 v[60:61], v[60:61], v[12:13] op_sel_hi:[1,0]
	v_pk_mul_f32 v[58:59], v[58:59], v[12:13] op_sel_hi:[1,0]
	v_pk_mul_f32 v[56:57], v[56:57], v[12:13] op_sel_hi:[1,0]
	v_pk_mul_f32 v[54:55], v[54:55], v[12:13] op_sel_hi:[1,0]
	v_pk_mul_f32 v[52:53], v[52:53], v[12:13] op_sel_hi:[1,0]
	v_pk_mul_f32 v[50:51], v[50:51], v[12:13] op_sel_hi:[1,0]
	v_pk_mul_f32 v[48:49], v[48:49], v[12:13] op_sel_hi:[1,0]
	v_pk_mul_f32 v[78:79], v[78:79], v[12:13] op_sel_hi:[1,0]
	v_pk_mul_f32 v[76:77], v[76:77], v[12:13] op_sel_hi:[1,0]
	v_pk_mul_f32 v[74:75], v[74:75], v[12:13] op_sel_hi:[1,0]
	v_pk_mul_f32 v[72:73], v[72:73], v[12:13] op_sel_hi:[1,0]
	v_pk_mul_f32 v[70:71], v[70:71], v[12:13] op_sel_hi:[1,0]
	v_pk_mul_f32 v[68:69], v[68:69], v[12:13] op_sel_hi:[1,0]
	v_pk_mul_f32 v[66:67], v[66:67], v[12:13] op_sel_hi:[1,0]
	v_pk_mul_f32 v[64:65], v[64:65], v[12:13] op_sel_hi:[1,0]
.Lattn_rare_a_1:
	v_cmp_lt_f32_e32 vcc, s97, v11
	s_cbranch_vccz .Lattn_rare_a_2
	v_max_f32_e32 v10, 0, v11
	v_exp_f32_e64 v12, -v10
	v_add_f32_e32 v219, v219, v10
	v_pk_add_f32 v[112:113], v[112:113], v[10:11] op_sel_hi:[1,0] neg_lo:[0,1] neg_hi:[0,1]
	v_pk_add_f32 v[114:115], v[114:115], v[10:11] op_sel_hi:[1,0] neg_lo:[0,1] neg_hi:[0,1]
	v_pk_add_f32 v[116:117], v[116:117], v[10:11] op_sel_hi:[1,0] neg_lo:[0,1] neg_hi:[0,1]
	v_pk_add_f32 v[118:119], v[118:119], v[10:11] op_sel_hi:[1,0] neg_lo:[0,1] neg_hi:[0,1]
	v_pk_add_f32 v[120:121], v[120:121], v[10:11] op_sel_hi:[1,0] neg_lo:[0,1] neg_hi:[0,1]
	v_pk_add_f32 v[122:123], v[122:123], v[10:11] op_sel_hi:[1,0] neg_lo:[0,1] neg_hi:[0,1]
	v_pk_add_f32 v[124:125], v[124:125], v[10:11] op_sel_hi:[1,0] neg_lo:[0,1] neg_hi:[0,1]
	v_pk_add_f32 v[126:127], v[126:127], v[10:11] op_sel_hi:[1,0] neg_lo:[0,1] neg_hi:[0,1]
	v_mul_f32_e32 v216, v216, v12
	v_pk_mul_f32 v[30:31], v[30:31], v[12:13] op_sel_hi:[1,0]
	v_pk_mul_f32 v[28:29], v[28:29], v[12:13] op_sel_hi:[1,0]
	v_pk_mul_f32 v[26:27], v[26:27], v[12:13] op_sel_hi:[1,0]
	v_pk_mul_f32 v[24:25], v[24:25], v[12:13] op_sel_hi:[1,0]
	v_pk_mul_f32 v[22:23], v[22:23], v[12:13] op_sel_hi:[1,0]
	v_pk_mul_f32 v[20:21], v[20:21], v[12:13] op_sel_hi:[1,0]
	v_pk_mul_f32 v[18:19], v[18:19], v[12:13] op_sel_hi:[1,0]
	v_pk_mul_f32 v[16:17], v[16:17], v[12:13] op_sel_hi:[1,0]
	v_pk_mul_f32 v[46:47], v[46:47], v[12:13] op_sel_hi:[1,0]
	v_pk_mul_f32 v[44:45], v[44:45], v[12:13] op_sel_hi:[1,0]
	v_pk_mul_f32 v[42:43], v[42:43], v[12:13] op_sel_hi:[1,0]
	v_pk_mul_f32 v[40:41], v[40:41], v[12:13] op_sel_hi:[1,0]
	v_pk_mul_f32 v[38:39], v[38:39], v[12:13] op_sel_hi:[1,0]
	v_pk_mul_f32 v[36:37], v[36:37], v[12:13] op_sel_hi:[1,0]
	v_pk_mul_f32 v[34:35], v[34:35], v[12:13] op_sel_hi:[1,0]
	v_pk_mul_f32 v[32:33], v[32:33], v[12:13] op_sel_hi:[1,0]

; __device__ void attn_phase(const Params& p, bool last, char* shm, int w0) {
;     ...
;     auto lstore = [&](int buf) {
;       *(u32x4*)(Ks + buf * 64 * KSTR + lk0) = rk0;
;       if (tid < 256) *(u32x4*)(Ks + buf * 64 * KSTR + lk1) = rk1;
;       *(u32x4*)(Vs + buf * 64 * VSTR + lv) = rv;
;     };
;     ...
;       if (kt + 1 < ntile) lstore(buf ^ 1);
;       __syncthreads();
.Lattn_body_end:
.LBB0_661:
	s_or_b64 exec, exec, s[0:1]
	s_xor_b32 s11, s11, 1
	s_mul_i32 s0, s11, 0x3400
	s_add_i32 s12, s0, 16
	v_lshl_add_u32 v0, v202, 1, s12
	s_waitcnt vmcnt(1)
	ds_write_b128 v0, v[2:5]
	s_and_saveexec_b64 s[0:1], s[6:7]
	s_cbranch_execz .LBB0_648
	v_lshl_add_u32 v0, v234, 1, s12
	ds_write_b128 v0, v[176:179] offset:128
	s_branch .LBB0_648
